# gates->merge barrier also XCD-local: B-finalize remapped so each XCD finalizes the tokens its own merge tiles read
# baseline (speedup 1.0000x reference)
.LBB0_582:
	s_or_b64 exec, exec, s[0:1]
	s_mov_b64 s[0:1], 0
	s_waitcnt lgkmcnt(0)
	s_barrier
	v_mov_b32_e32 v0, v197
	s_add_u32 s0, s96, s0
	s_addc_u32 s1, s97, s1
	s_and_b32 s2, s52, 7
	s_lshl_b32 s2, s2, 16
	s_lshr_b32 s3, s52, 3
	s_lshl_b32 s3, s3, 11
	s_add_i32 s2, s2, s3
	v_add_u32_e32 v66, s2, v0
	v_cmp_gt_i32_e32 vcc, s80, v66
	s_and_saveexec_b64 s[10:11], vcc
	s_cbranch_execz .LBB0_597
	s_add_u32 s12, s0, 0x7800000
	s_addc_u32 s13, s1, 0
	v_readlane_b32 s2, v253, 62
	s_add_u32 s14, s0, 0x10900000
	s_addc_u32 s15, s1, 0
	v_lshl_add_u32 v76, v0, 3, s2
	v_mov_b32_e32 v0, 0
	s_mov_b64 s[16:17], 0
	v_mov_b32_e32 v1, v0
	v_mov_b32_e32 v2, v0
	v_mov_b32_e32 v3, v0
	v_mov_b32_e32 v16, v0
	v_mov_b32_e32 v17, v0
	v_mov_b32_e32 v18, v0
	v_mov_b32_e32 v19, v0
	v_mov_b32_e32 v32, v0
	v_mov_b32_e32 v33, v0
	v_mov_b32_e32 v34, v0
	v_mov_b32_e32 v35, v0
	v_mov_b32_e32 v36, v0
	v_mov_b32_e32 v37, v0
	v_mov_b32_e32 v38, v0
	v_mov_b32_e32 v39, v0
	v_mov_b32_e32 v40, v0
	v_mov_b32_e32 v41, v0
	v_mov_b32_e32 v42, v0
	v_mov_b32_e32 v43, v0
	v_mov_b32_e32 v44, v0
	v_mov_b32_e32 v45, v0
	v_mov_b32_e32 v46, v0
	v_mov_b32_e32 v47, v0
	s_branch .LBB0_585
.LBB0_584:
	s_or_b64 exec, exec, s[6:7]
	s_add_i32 s2, s61, s61
	s_add_i32 s2, s2, s61
	v_add_u32_e32 v66, s2, v86
	s_mov_b32 s2, -1
	v_cmp_lt_i32_e32 vcc, s2, v66
	s_or_b64 s[16:17], vcc, s[16:17]
	v_add_u32_e32 v76, s70, v76
	s_andn2_b64 exec, exec, s[16:17]
	s_cbranch_execz .LBB0_597
.LBB0_585:
	v_ashrrev_i32_e32 v60, 5, v66
	v_bfe_u32 v67, v66, 3, 2
	v_ashrrev_i32_e32 v61, 31, v60
	v_lshl_add_u64 v[48:49], v[60:61], 4, s[14:15]
	v_lshlrev_b32_e32 v194, 2, v67
	v_lshl_add_u64 v[48:49], v[48:49], 0, v[194:195]
	s_mov_b32 s2, 0x40000
	v_add_co_u32_e32 v50, vcc, s2, v48
	v_mov_b64_e32 v[54:55], s[12:13]
	v_and_b32_e32 v56, 56, v76
	v_addc_co_u32_e32 v51, vcc, 0, v49, vcc
	v_mad_i64_i32 v[54:55], s[2:3], v60, s99, v[54:55]
	v_lshlrev_b32_e32 v62, 7, v67
	v_mov_b32_e32 v63, v195
	v_add_co_u32_e32 v52, vcc, s80, v48
	v_lshl_add_u64 v[54:55], v[54:55], 0, v[62:63]
	v_lshlrev_b32_e32 v64, 1, v56
	v_mov_b32_e32 v65, v195
	v_lshlrev_b64 v[60:61], 11, v[60:61]
	v_addc_co_u32_e32 v53, vcc, 0, v49, vcc
	v_lshl_add_u64 v[56:57], v[54:55], 0, v[64:65]
	v_lshl_add_u64 v[72:73], s[0:1], 0, v[60:61]
	global_load_dword v89, v[48:49], off
	global_load_dword v88, v[50:51], off
	global_load_dword v87, v[52:53], off
	s_nop 0
	global_load_dwordx4 v[48:51], v[56:57], off
	global_load_dwordx4 v[52:55], v[56:57], off offset:512
	s_nop 0
	global_load_dwordx4 v[56:59], v[56:57], off offset:1024
	v_lshl_add_u64 v[60:61], v[72:73], 0, v[62:63]
	v_lshl_add_u64 v[60:61], v[60:61], 0, v[64:65]
	v_add_co_u32_e32 v60, vcc, 0x9000000, v60
	v_add_u32_e32 v86, 0x200, v66
	s_nop 0
	v_addc_co_u32_e32 v61, vcc, 0, v61, vcc
	global_load_dwordx4 v[60:63], v[60:61], off offset:1024
	v_lshlrev_b32_e32 v67, 6, v67
	v_ashrrev_i32_e32 v70, 5, v86
	v_cmp_gt_i32_e64 s[8:9], s80, v86
	v_ashrrev_i32_e32 v71, 31, v70
	v_lshlrev_b32_e32 v74, 1, v67
	s_and_saveexec_b64 s[4:5], s[8:9]
	s_cbranch_execz .LBB0_587
	v_lshl_add_u64 v[0:1], v[70:71], 4, s[14:15]
	v_lshl_add_u64 v[0:1], v[0:1], 0, v[194:195]
	v_add_co_u32_e32 v2, vcc, 0x40000, v0
	s_waitcnt vmcnt(8)
	v_mov_b64_e32 v[6:7], s[12:13]
	v_addc_co_u32_e32 v3, vcc, 0, v1, vcc
	v_mad_i64_i32 v[6:7], s[2:3], v70, s99, v[6:7]
	v_mov_b32_e32 v75, v195
	v_add_co_u32_e32 v4, vcc, 0x80000, v0
	v_lshl_add_u64 v[6:7], v[6:7], 0, v[74:75]
	v_lshlrev_b64 v[20:21], 11, v[70:71]
	v_addc_co_u32_e32 v5, vcc, 0, v1, vcc
	v_lshl_add_u64 v[6:7], v[6:7], 0, v[64:65]
	v_lshl_add_u64 v[20:21], s[0:1], 0, v[20:21]
	global_load_dword v77, v[0:1], off
	global_load_dword v80, v[2:3], off
	global_load_dword v83, v[4:5], off
	s_nop 0
	global_load_dwordx4 v[0:3], v[6:7], off
	global_load_dwordx4 v[36:39], v[6:7], off offset:512
	s_nop 0
	global_load_dwordx4 v[4:7], v[6:7], off offset:1024
	v_lshl_add_u64 v[20:21], v[20:21], 0, v[74:75]
	v_lshl_add_u64 v[20:21], v[20:21], 0, v[64:65]
	v_add_co_u32_e32 v20, vcc, s79, v20
	s_nop 1
	v_addc_co_u32_e32 v21, vcc, 0, v21, vcc
	global_load_dwordx4 v[20:23], v[20:21], off offset:1024
.LBB0_587:
	s_or_b64 exec, exec, s[4:5]
	v_add_u32_e32 v65, 0x400, v66
	v_ashrrev_i32_e32 v68, 5, v65
	v_cmp_gt_i32_e64 s[6:7], s80, v65
	v_ashrrev_i32_e32 v69, 31, v68
	s_and_saveexec_b64 s[4:5], s[6:7]
	s_cbranch_execz .LBB0_589
	v_lshl_add_u64 v[12:13], v[68:69], 4, s[14:15]
	v_lshl_add_u64 v[12:13], v[12:13], 0, v[194:195]
	v_add_co_u32_e32 v14, vcc, 0x40000, v12
	v_mov_b64_e32 v[18:19], s[12:13]
	s_nop 0
	v_addc_co_u32_e32 v15, vcc, 0, v13, vcc
	v_mad_i64_i32 v[18:19], s[2:3], v68, s99, v[18:19]
	v_mov_b32_e32 v75, v195
	v_add_co_u32_e32 v16, vcc, 0x80000, v12
	v_lshl_add_u64 v[18:19], v[18:19], 0, v[74:75]
	v_mov_b32_e32 v65, v195
	v_addc_co_u32_e32 v17, vcc, 0, v13, vcc
	v_lshl_add_u64 v[28:29], v[18:19], 0, v[64:65]
	global_load_dword v79, v[12:13], off
	global_load_dword v82, v[14:15], off
	global_load_dword v85, v[16:17], off
	s_nop 0
	global_load_dwordx4 v[16:19], v[28:29], off
	global_load_dwordx4 v[40:43], v[28:29], off offset:512
	global_load_dwordx4 v[12:15], v[28:29], off offset:1024
	v_lshlrev_b64 v[28:29], 11, v[68:69]
	v_lshl_add_u64 v[28:29], s[0:1], 0, v[28:29]
	v_lshl_add_u64 v[28:29], v[28:29], 0, v[74:75]
	v_lshl_add_u64 v[28:29], v[28:29], 0, v[64:65]
	v_add_co_u32_e32 v28, vcc, s79, v28
	s_nop 1
	v_addc_co_u32_e32 v29, vcc, 0, v29, vcc
	global_load_dwordx4 v[28:31], v[28:29], off offset:1024
.LBB0_589:
	s_or_b64 exec, exec, s[4:5]
	s_movk_i32 s2, 0x600
	v_add_u32_e32 v65, s2, v66
	v_ashrrev_i32_e32 v66, 5, v65
	v_cmp_gt_i32_e64 s[4:5], s80, v65
	v_ashrrev_i32_e32 v67, 31, v66
	s_and_saveexec_b64 s[18:19], s[4:5]
	s_cbranch_execz .LBB0_591
	v_lshl_add_u64 v[8:9], v[66:67], 4, s[14:15]
	v_lshl_add_u64 v[8:9], v[8:9], 0, v[194:195]
	v_add_co_u32_e32 v10, vcc, 0x40000, v8
	v_mov_b64_e32 v[26:27], s[12:13]
	s_nop 0
	v_addc_co_u32_e32 v11, vcc, 0, v9, vcc
	v_add_co_u32_e32 v24, vcc, 0x80000, v8
	v_mad_i64_i32 v[26:27], s[2:3], v66, s99, v[26:27]
	v_mov_b32_e32 v75, v195
	v_addc_co_u32_e32 v25, vcc, 0, v9, vcc
	v_lshl_add_u64 v[26:27], v[26:27], 0, v[74:75]
	v_mov_b32_e32 v65, v195
	v_lshl_add_u64 v[26:27], v[26:27], 0, v[64:65]
	global_load_dword v78, v[8:9], off
	global_load_dword v81, v[10:11], off
	global_load_dword v84, v[24:25], off
	global_load_dwordx4 v[32:35], v[26:27], off
	global_load_dwordx4 v[44:47], v[26:27], off offset:512
	s_nop 0
	global_load_dwordx4 v[8:11], v[26:27], off offset:1024
	v_lshlrev_b64 v[24:25], 11, v[66:67]
	v_lshl_add_u64 v[24:25], s[0:1], 0, v[24:25]
	v_lshl_add_u64 v[24:25], v[24:25], 0, v[74:75]
	v_lshl_add_u64 v[24:25], v[24:25], 0, v[64:65]
	v_add_co_u32_e32 v24, vcc, s79, v24
	s_nop 1
	v_addc_co_u32_e32 v25, vcc, 0, v25, vcc
	global_load_dwordx4 v[24:27], v[24:25], off offset:1024

.LBB0_641:
	s_andn2_saveexec_b64 s[6:7], s[6:7]
	s_cbranch_execz .LBB0_661
	s_mov_b64 s[6:7], exec
	v_readfirstlane_b32 s3, v254
	s_nop 3
	s_cmp_eq_u32 s3, 0
	s_cbranch_scc1 .LBB0_658
	buffer_wbl2 sc1
	s_waitcnt lgkmcnt(0)
	s_waitcnt vmcnt(0)
	v_mbcnt_lo_u32_b32 v1, s6, 0
	v_mbcnt_hi_u32_b32 v1, s7, v1
	v_cmp_eq_u32_e32 vcc, 0, v1
	s_and_saveexec_b64 s[8:9], vcc
	s_cbranch_execz .LBB0_644
	s_bcnt1_i32_b64 s3, s[6:7]
	v_mov_b32_e32 v2, s3
	global_atomic_add v2, v220, v2, s[4:5] offset:1024 sc0
